# MFMA-LDS interleave in neighbourhood-attention tile loop (B-operand ds_reads prefetched 4 deep, batched rel-pos bias) and batched decay-mask LDS reads in the DeltaNet scan
# speedup vs baseline: 1.0132x; 1.0132x over previous
.LBB0_669:
	v_max_f32_e32 v80, v166, v166
	v_max_f32_e32 v81, v169, v169
	v_max_f32_e32 v80, v81, v80
	v_max3_f32 v80, v170, v168, v80
	v_lshl_add_u32 v82, v108, 1, v97
	v_lshlrev_b32_e32 v84, 1, v111
	v_mov_b32_dpp v81, v80 quad_perm:[1,0,3,2] row_mask:0xf bank_mask:0xf bound_ctrl:1
	v_max_f32_e32 v81, v81, v81
	v_max_f32_e32 v80, v80, v81
	v_add3_u32 v83, v82, v84, v120
	v_max_f32_e32 v86, v165, v165
	v_mov_b32_dpp v81, v80 quad_perm:[2,3,0,1] row_mask:0xf bank_mask:0xf bound_ctrl:1
	v_max_f32_e32 v81, v81, v81
	v_max_f32_e32 v80, v80, v81
	v_max_f32_e32 v91, v93, v93
	s_addk_i32 s37, 0x7c
	v_mov_b32_dpp v81, v80 row_half_mirror row_mask:0xf bank_mask:0xf bound_ctrl:1
	v_max_f32_e32 v81, v81, v81
	v_max_f32_e32 v80, v80, v81
	s_add_i32 s36, s36, 1
	s_mul_i32 s76, s35, 0x7c
	v_mov_b32_dpp v81, v80 row_mirror row_mask:0xf bank_mask:0xf bound_ctrl:1
	v_max3_f32 v85, v144, v80, v81
	v_sub_f32_e32 v80, v144, v85
	v_exp_f32_e32 v81, v80
	v_sub_f32_e32 v80, v170, v85
	v_exp_f32_e32 v95, v80
	v_add_u32_e32 v106, 64, v106
	s_cmp_lg_u32 s76, s37
	v_bfe_u32 v80, v95, 16, 1
	v_add3_u32 v80, v95, v80, s26
	ds_write_b16_d16_hi v83, v80
	v_sub_f32_e32 v80, v168, v85
	v_exp_f32_e32 v171, v80
	s_nop 0
	v_bfe_u32 v80, v171, 16, 1
	v_add3_u32 v80, v171, v80, s26
	ds_write_b16_d16_hi v83, v80 offset:32
	v_sub_f32_e32 v80, v169, v85
	v_exp_f32_e32 v169, v80
	s_nop 0
	v_bfe_u32 v80, v169, 16, 1
	v_add3_u32 v80, v169, v80, s26
	ds_write_b16_d16_hi v83, v80 offset:64
	v_sub_f32_e32 v80, v166, v85
	v_exp_f32_e32 v173, v80
	s_nop 0
	v_bfe_u32 v80, v173, 16, 1
	v_add3_u32 v80, v173, v80, s26
	ds_write_b16_d16_hi v83, v80 offset:96
	v_max_f32_e32 v80, v146, v146
	v_max_f32_e32 v80, v86, v80
	v_max3_f32 v80, v167, v147, v80
	s_nop 1
	v_mov_b32_dpp v86, v80 quad_perm:[1,0,3,2] row_mask:0xf bank_mask:0xf bound_ctrl:1
	v_max_f32_e32 v86, v86, v86
	v_max_f32_e32 v80, v80, v86
	s_nop 1
	v_mov_b32_dpp v86, v80 quad_perm:[2,3,0,1] row_mask:0xf bank_mask:0xf bound_ctrl:1
	v_max_f32_e32 v86, v86, v86
	v_max_f32_e32 v80, v80, v86
	s_nop 1
	v_mov_b32_dpp v86, v80 row_half_mirror row_mask:0xf bank_mask:0xf bound_ctrl:1
	v_max_f32_e32 v86, v86, v86
	v_max_f32_e32 v80, v80, v86
	s_nop 1
	v_mov_b32_dpp v86, v80 row_mirror row_mask:0xf bank_mask:0xf bound_ctrl:1
	v_max3_f32 v86, v143, v80, v86
	v_sub_f32_e32 v87, v167, v86
	v_exp_f32_e32 v94, v87
	v_sub_f32_e32 v80, v143, v86
	v_exp_f32_e32 v80, v80
	v_bfe_u32 v87, v94, 16, 1
	v_add3_u32 v87, v94, v87, s26
	ds_write_b16_d16_hi v83, v87 offset:144
	v_sub_f32_e32 v87, v147, v86
	v_exp_f32_e32 v170, v87
	v_pk_add_f32 v[94:95], v[94:95], 0 op_sel_hi:[1,0]
	v_bfe_u32 v87, v170, 16, 1
	v_add3_u32 v87, v170, v87, s26
	ds_write_b16_d16_hi v83, v87 offset:176
	v_sub_f32_e32 v87, v165, v86
	v_exp_f32_e32 v168, v87
	v_pk_add_f32 v[94:95], v[170:171], v[94:95]
	v_bfe_u32 v87, v168, 16, 1
	v_add3_u32 v87, v168, v87, s26
	ds_write_b16_d16_hi v83, v87 offset:208
	v_sub_f32_e32 v87, v146, v86
	v_exp_f32_e32 v172, v87
	v_pk_add_f32 v[94:95], v[168:169], v[94:95]
	v_bfe_u32 v87, v172, 16, 1
	v_add3_u32 v87, v172, v87, s26
	ds_write_b16_d16_hi v83, v87 offset:240
	v_max_f32_e32 v87, v109, v109
	v_max_f32_e32 v87, v91, v87
	v_max3_f32 v87, v145, v88, v87
	v_pk_add_f32 v[94:95], v[172:173], v[94:95]
	s_nop 0
	v_mov_b32_dpp v91, v87 quad_perm:[1,0,3,2] row_mask:0xf bank_mask:0xf bound_ctrl:1
	v_max_f32_e32 v91, v91, v91
	v_max_f32_e32 v87, v87, v91
	v_pk_fma_f32 v[104:105], v[104:105], v[80:81], v[94:95]
	s_nop 0
	v_mov_b32_dpp v91, v87 quad_perm:[2,3,0,1] row_mask:0xf bank_mask:0xf bound_ctrl:1
	v_max_f32_e32 v91, v91, v91
	v_max_f32_e32 v87, v87, v91
	s_nop 1
	v_mov_b32_dpp v91, v87 row_half_mirror row_mask:0xf bank_mask:0xf bound_ctrl:1
	v_max_f32_e32 v91, v91, v91
	v_max_f32_e32 v87, v87, v91
	s_nop 1
	v_mov_b32_dpp v91, v87 row_mirror row_mask:0xf bank_mask:0xf bound_ctrl:1
	v_max3_f32 v87, v142, v87, v91
	v_sub_f32_e32 v88, v88, v87
	v_sub_f32_e32 v91, v142, v87
	v_exp_f32_e32 v142, v88
	v_exp_f32_e32 v94, v91
	v_sub_f32_e32 v91, v145, v87
	v_exp_f32_e32 v108, v91
	v_bfe_u32 v88, v142, 16, 1
	v_add3_u32 v88, v142, v88, s26
	ds_write_b16_d16_hi v83, v88 offset:320
	v_sub_f32_e32 v88, v93, v87
	v_exp_f32_e32 v144, v88
	v_bfe_u32 v91, v108, 16, 1
	v_add3_u32 v91, v108, v91, s26
	ds_write_b16_d16_hi v83, v91 offset:288
	v_bfe_u32 v88, v144, 16, 1
	v_add3_u32 v88, v144, v88, s26
	ds_write_b16_d16_hi v83, v88 offset:352
	v_sub_f32_e32 v88, v109, v87
	v_exp_f32_e32 v146, v88
	v_max_f32_e32 v91, v92, v92
	v_bfe_u32 v88, v146, 16, 1
	v_add3_u32 v88, v146, v88, s26
	ds_write_b16_d16_hi v83, v88 offset:384
	v_max_f32_e32 v88, v107, v107
	v_max_f32_e32 v88, v91, v88
	v_max3_f32 v88, v90, v89, v88
	s_nop 1
	v_mov_b32_dpp v91, v88 quad_perm:[1,0,3,2] row_mask:0xf bank_mask:0xf bound_ctrl:1
	v_max_f32_e32 v91, v91, v91
	v_max_f32_e32 v88, v88, v91
	s_nop 1
	v_mov_b32_dpp v91, v88 quad_perm:[2,3,0,1] row_mask:0xf bank_mask:0xf bound_ctrl:1
	v_max_f32_e32 v91, v91, v91
	v_max_f32_e32 v88, v88, v91
	s_nop 1
	v_mov_b32_dpp v91, v88 row_half_mirror row_mask:0xf bank_mask:0xf bound_ctrl:1
	v_max_f32_e32 v91, v91, v91
	v_max_f32_e32 v88, v88, v91
	s_nop 1
	v_mov_b32_dpp v91, v88 row_mirror row_mask:0xf bank_mask:0xf bound_ctrl:1
	v_max3_f32 v88, v141, v88, v91
	v_sub_f32_e32 v89, v89, v88
	v_exp_f32_e32 v143, v89
	v_sub_f32_e32 v90, v90, v88
	v_exp_f32_e32 v109, v90
	v_sub_f32_e32 v91, v141, v88
	v_bfe_u32 v89, v143, 16, 1
	v_add3_u32 v89, v143, v89, s26
	ds_write_b16_d16_hi v83, v89 offset:464
	v_sub_f32_e32 v89, v92, v88
	v_exp_f32_e32 v145, v89
	v_bfe_u32 v90, v109, 16, 1
	v_add3_u32 v90, v109, v90, s26
	v_exp_f32_e32 v95, v91
	v_bfe_u32 v89, v145, 16, 1
	v_add3_u32 v89, v145, v89, s26
	ds_write_b16_d16_hi v83, v89 offset:496
	v_sub_f32_e32 v89, v107, v88
	v_exp_f32_e32 v147, v89
	ds_write_b16_d16_hi v83, v90 offset:432
	v_pk_add_f32 v[90:91], v[108:109], 0 op_sel_hi:[1,0]
	v_pk_mul_f32 v[54:55], v[54:55], v[94:95]
	v_pk_add_f32 v[90:91], v[142:143], v[90:91]
	v_bfe_u32 v89, v147, 16, 1
	v_pk_add_f32 v[90:91], v[144:145], v[90:91]
	v_add3_u32 v89, v147, v89, s26
	v_pk_add_f32 v[90:91], v[146:147], v[90:91]
	ds_write_b16_d16_hi v83, v89 offset:528
	v_pk_fma_f32 v[98:99], v[98:99], v[94:95], v[90:91]
	v_mov_b32_e32 v90, v81
	v_mov_b32_e32 v91, v80
	v_add3_u32 v80, v82, v117, v112
	v_add3_u32 v89, v140, v112, v121
	v_pk_mul_f32 v[52:53], v[52:53], v[90:91]
	v_pk_mul_f32 v[56:57], v[56:57], v[90:91]
	v_pk_mul_f32 v[60:61], v[60:61], v[90:91]
	v_pk_mul_f32 v[64:65], v[64:65], v[90:91]
	v_pk_mul_f32 v[68:69], v[68:69], v[90:91]
	v_pk_mul_f32 v[72:73], v[72:73], v[90:91]
	v_pk_mul_f32 v[76:77], v[76:77], v[90:91]
	v_pk_mul_f32 v[36:37], v[36:37], v[90:91]
	ds_read_b128 v[90:93], v80
	ds_read_b128 v[80:83], v80 offset:64
	ds_read_b128 v[232:235], v89
	ds_read_b128 v[236:239], v89 offset:64
	ds_read_b128 v[240:243], v89 offset:2304
	ds_read_b128 v[244:247], v89 offset:2368
	ds_read_b128 v[248:251], v89 offset:4608
	s_waitcnt lgkmcnt(4)
	v_mfma_f32_16x16x32_bf16 v[52:55], v[90:93], v[232:235], v[52:55]
	v_pk_mul_f32 v[58:59], v[58:59], v[94:95]
	v_pk_mul_f32 v[62:63], v[62:63], v[94:95]
	ds_read_b128 v[232:235], v89 offset:4672
	s_waitcnt lgkmcnt(4)
	v_mfma_f32_16x16x32_bf16 v[52:55], v[80:83], v[236:239], v[52:55]
	v_pk_mul_f32 v[66:67], v[66:67], v[94:95]
	v_pk_mul_f32 v[70:71], v[70:71], v[94:95]
	ds_read_b128 v[236:239], v89 offset:6912
	s_waitcnt lgkmcnt(4)
	v_mfma_f32_16x16x32_bf16 v[56:59], v[90:93], v[240:243], v[56:59]
	v_pk_mul_f32 v[74:75], v[74:75], v[94:95]
	v_pk_mul_f32 v[78:79], v[78:79], v[94:95]
	ds_read_b128 v[240:243], v89 offset:6976
	s_waitcnt lgkmcnt(4)
	v_mfma_f32_16x16x32_bf16 v[56:59], v[80:83], v[244:247], v[56:59]
	v_pk_mul_f32 v[38:39], v[38:39], v[94:95]
	v_mov_b32_e32 v144, v85
	ds_read_b128 v[244:247], v89 offset:9216
	s_waitcnt lgkmcnt(4)
	v_mfma_f32_16x16x32_bf16 v[60:63], v[90:93], v[248:251], v[60:63]
	ds_read_b128 v[248:251], v89 offset:9280
	s_waitcnt lgkmcnt(4)
	v_mfma_f32_16x16x32_bf16 v[60:63], v[80:83], v[232:235], v[60:63]
	ds_read_b128 v[232:235], v89 offset:11520
	s_waitcnt lgkmcnt(4)
	v_mfma_f32_16x16x32_bf16 v[64:67], v[90:93], v[236:239], v[64:67]
	ds_read_b128 v[236:239], v89 offset:11584
	s_waitcnt lgkmcnt(4)
	v_mfma_f32_16x16x32_bf16 v[64:67], v[80:83], v[240:243], v[64:67]
	ds_read_b128 v[240:243], v89 offset:13824
	s_waitcnt lgkmcnt(4)
	v_mfma_f32_16x16x32_bf16 v[68:71], v[90:93], v[244:247], v[68:71]
	ds_read_b128 v[244:247], v89 offset:13888
	s_waitcnt lgkmcnt(4)
	v_mfma_f32_16x16x32_bf16 v[68:71], v[80:83], v[248:251], v[68:71]
	ds_read_b128 v[248:251], v89 offset:16128
	s_waitcnt lgkmcnt(4)
	v_mfma_f32_16x16x32_bf16 v[72:75], v[90:93], v[232:235], v[72:75]
	ds_read_b128 v[232:235], v89 offset:16192
	s_waitcnt lgkmcnt(4)
	v_mfma_f32_16x16x32_bf16 v[72:75], v[80:83], v[236:239], v[72:75]
	s_waitcnt lgkmcnt(3)
	v_mfma_f32_16x16x32_bf16 v[76:79], v[90:93], v[240:243], v[76:79]
	s_waitcnt lgkmcnt(2)
	v_mfma_f32_16x16x32_bf16 v[76:79], v[80:83], v[244:247], v[76:79]
	s_waitcnt lgkmcnt(1)
	v_mfma_f32_16x16x32_bf16 v[36:39], v[90:93], v[248:251], v[36:39]
	v_mov_b32_e32 v143, v86
	v_mov_b32_e32 v142, v87
	s_waitcnt lgkmcnt(0)
	v_mfma_f32_16x16x32_bf16 v[36:39], v[80:83], v[232:235], v[36:39]
	v_mov_b32_e32 v141, v88
	s_cbranch_scc0 .LBB0_712

.LBB0_678:
	v_add3_u32 v107, v80, v112, v119
	s_cmp_gt_u32 s80, 3
	s_cselect_b64 s[76:77], -1, 0
	s_and_b64 s[76:77], s[38:39], s[76:77]
	s_andn2_b64 vcc, exec, s[76:77]
	ds_read_b128 v[232:235], v107 offset:34816
	ds_read_b128 v[236:239], v107 offset:34880
	ds_read_b128 v[240:243], v107 offset:34944
	ds_read_b128 v[244:247], v107 offset:35008
	ds_read_b128 v[248:251], v107 offset:39168
	s_waitcnt lgkmcnt(4)
	v_mfma_f32_16x16x32_bf16 v[80:83], v[0:3], v[232:235], 0
	ds_read_b128 v[232:235], v107 offset:39232
	s_waitcnt lgkmcnt(4)
	v_mfma_f32_16x16x32_bf16 v[80:83], v[4:7], v[236:239], v[80:83]
	ds_read_b128 v[236:239], v107 offset:39296
	s_waitcnt lgkmcnt(4)
	v_mfma_f32_16x16x32_bf16 v[80:83], v[8:11], v[240:243], v[80:83]
	ds_read_b128 v[240:243], v107 offset:39360
	s_waitcnt lgkmcnt(4)
	v_mfma_f32_16x16x32_bf16 v[80:83], v[12:15], v[244:247], v[80:83]
	ds_read_b128 v[244:247], v107 offset:43520
	s_waitcnt lgkmcnt(4)
	v_mfma_f32_16x16x32_bf16 v[84:87], v[0:3], v[248:251], 0
	ds_read_b128 v[248:251], v107 offset:43584
	s_waitcnt lgkmcnt(4)
	v_mfma_f32_16x16x32_bf16 v[84:87], v[4:7], v[232:235], v[84:87]
	ds_read_b128 v[232:235], v107 offset:43648
	s_waitcnt lgkmcnt(4)
	v_mfma_f32_16x16x32_bf16 v[84:87], v[8:11], v[236:239], v[84:87]
	ds_read_b128 v[236:239], v107 offset:43712
	s_waitcnt lgkmcnt(4)
	v_mfma_f32_16x16x32_bf16 v[84:87], v[12:15], v[240:243], v[84:87]
	ds_read_b128 v[240:243], v107 offset:47872
	s_waitcnt lgkmcnt(4)
	v_mfma_f32_16x16x32_bf16 v[88:91], v[0:3], v[244:247], 0
	ds_read_b128 v[244:247], v107 offset:47936
	s_waitcnt lgkmcnt(4)
	v_mfma_f32_16x16x32_bf16 v[88:91], v[4:7], v[248:251], v[88:91]
	ds_read_b128 v[248:251], v107 offset:48000
	s_waitcnt lgkmcnt(4)
	v_mfma_f32_16x16x32_bf16 v[88:91], v[8:11], v[232:235], v[88:91]
	ds_read_b128 v[232:235], v107 offset:48064
	s_waitcnt lgkmcnt(4)
	v_mfma_f32_16x16x32_bf16 v[88:91], v[12:15], v[236:239], v[88:91]
	s_waitcnt lgkmcnt(3)
	v_mfma_f32_16x16x32_bf16 v[92:95], v[0:3], v[240:243], 0
	s_waitcnt lgkmcnt(2)
	v_mfma_f32_16x16x32_bf16 v[92:95], v[4:7], v[244:247], v[92:95]
	s_waitcnt lgkmcnt(1)
	v_mfma_f32_16x16x32_bf16 v[92:95], v[8:11], v[248:251], v[92:95]
	s_waitcnt lgkmcnt(0)
	v_mfma_f32_16x16x32_bf16 v[92:95], v[12:15], v[232:235], v[92:95]
	s_cbranch_vccnz .LBB0_711
	v_add_u32_e32 v232, s37, v139
	ds_read_b32 v232, v232
	v_add_u32_e32 v233, s37, v138
	ds_read_b32 v233, v233
	v_add_u32_e32 v234, s37, v137
	ds_read_b32 v234, v234
	v_add_u32_e32 v235, s37, v136
	ds_read_b32 v235, v235
	v_add_u32_e32 v236, s37, v135
	ds_read_b32 v236, v236
	v_add_u32_e32 v237, s37, v134
	ds_read_b32 v237, v237
	v_add_u32_e32 v238, s37, v133
	ds_read_b32 v238, v238
	v_add_u32_e32 v239, s37, v132
	ds_read_b32 v239, v239
	v_add_u32_e32 v240, s37, v131
	ds_read_b32 v240, v240
	v_add_u32_e32 v241, s37, v130
	ds_read_b32 v241, v241
	v_add_u32_e32 v242, s37, v127
	ds_read_b32 v242, v242
	v_add_u32_e32 v243, s37, v126
	ds_read_b32 v243, v243
	v_add_u32_e32 v244, s37, v125
	ds_read_b32 v244, v244
	v_add_u32_e32 v245, s37, v124
	ds_read_b32 v245, v245
	v_add_u32_e32 v246, s37, v123
	ds_read_b32 v246, v246
	v_add_u32_e32 v247, s37, v122
	ds_read_b32 v247, v247
	v_mov_b32_e32 v248, 0xf149f2ca
	s_waitcnt lgkmcnt(0)
	v_add_f32_e32 v232, v80, v232
	v_add_f32_e32 v233, v84, v233
	v_add_f32_e32 v234, v88, v234
	v_add_f32_e32 v235, v92, v235
	v_add_f32_e32 v236, v81, v236
	v_add_f32_e32 v237, v85, v237
	v_add_f32_e32 v238, v89, v238
	v_add_f32_e32 v239, v93, v239
	v_add_f32_e32 v240, v82, v240
	v_add_f32_e32 v241, v86, v241
	v_add_f32_e32 v242, v90, v242
	v_add_f32_e32 v243, v94, v243
	v_add_f32_e32 v244, v83, v244
	v_add_f32_e32 v245, v87, v245
	v_add_f32_e32 v246, v91, v246
	v_add_f32_e32 v247, v95, v247
	v_cndmask_b32_e64 v170, v248, v232, s[40:41]
	v_cndmask_b32_e64 v168, v248, v233, s[60:61]
	v_cndmask_b32_e64 v169, v248, v234, s[62:63]
	v_cndmask_b32_e64 v166, v248, v235, s[42:43]
	v_cndmask_b32_e64 v167, v248, v236, s[44:45]
	v_cndmask_b32_e64 v147, v248, v237, s[64:65]
	v_cndmask_b32_e64 v165, v248, v238, s[66:67]
	v_cndmask_b32_e64 v146, v248, v239, s[46:47]
	v_cndmask_b32_e64 v145, v248, v240, s[48:49]
	v_cndmask_b32_e64 v88, v248, v241, s[68:69]
	v_cndmask_b32_e64 v93, v248, v242, s[70:71]
	v_cndmask_b32_e64 v109, v248, v243, s[50:51]
	v_cndmask_b32_e64 v90, v248, v244, s[52:53]
	v_cndmask_b32_e64 v89, v248, v245, s[72:73]
	v_cndmask_b32_e64 v92, v248, v246, s[74:75]
	v_cndmask_b32_e64 v107, v248, v247, s[54:55]
	s_branch .LBB0_669

.LBB0_759:
	v_add_u32_e32 v32, 0x24cfc, v194
	ds_read_b32 v195, v32
	v_add_u32_e32 v196, 0x19800, v194
	s_and_saveexec_b64 s[82:83], s[44:45]
	s_cbranch_execz .LBB0_752
	v_add_u32_e32 v32, v194, v105
	v_add3_u32 v62, v32, v192, v193
	ds_read_b128 v[32:35], v62 offset:34816
	v_add_u32_e32 v36, v194, v118
	v_add3_u32 v63, v36, v192, v193
	ds_read_b128 v[36:39], v63 offset:52224
	ds_read_b128 v[50:53], v62 offset:34848
	ds_read_b128 v[54:57], v63 offset:52256
	ds_read_b128 v[58:61], v62 offset:34880
	ds_read_b128 v[200:203], v63 offset:52288
	ds_read_b128 v[204:207], v62 offset:34912
	ds_read_b128 v[208:211], v63 offset:52320
	s_waitcnt lgkmcnt(6)
	v_mfma_f32_32x32x16_bf16 v[32:47], v[32:35], v[36:39], 0
	s_waitcnt lgkmcnt(4)
	v_mfma_f32_32x32x16_bf16 v[32:47], v[50:53], v[54:57], v[32:47]
	s_waitcnt lgkmcnt(2)
	v_mfma_f32_32x32x16_bf16 v[32:47], v[58:61], v[200:203], v[32:47]
	s_waitcnt lgkmcnt(0)
	v_mfma_f32_32x32x16_bf16 v[32:47], v[204:207], v[208:211], v[32:47]
	ds_read_b128 v[50:53], v62 offset:34944
	ds_read_b128 v[58:61], v63 offset:52352
	ds_read_b128 v[54:57], v62 offset:34976
	ds_read_b128 v[200:203], v63 offset:52384
	ds_read_b128 v[204:207], v62 offset:35008
	ds_read_b128 v[208:211], v63 offset:52416
	ds_read_b128 v[212:215], v62 offset:35040
	ds_read_b128 v[216:219], v63 offset:52448
	s_waitcnt lgkmcnt(6)
	v_mfma_f32_32x32x16_bf16 v[32:47], v[50:53], v[58:61], v[32:47]
	v_lshl_add_u32 v50, v119, 2, v49
	ds_read_b32 v50, v50
	v_mov_b32_e32 v51, 0
	v_mov_b32_e32 v52, 0
	s_waitcnt lgkmcnt(5)
	v_mfma_f32_32x32x16_bf16 v[32:47], v[54:57], v[200:203], v[32:47]
	s_waitcnt lgkmcnt(3)
	v_mfma_f32_32x32x16_bf16 v[32:47], v[204:207], v[208:211], v[32:47]
	s_waitcnt lgkmcnt(1)
	v_mfma_f32_32x32x16_bf16 v[32:47], v[212:215], v[216:219], v[32:47]
	v_lshl_add_u32 v232, v120, 2, v49
	ds_read_b32 v232, v232
	v_lshl_add_u32 v233, v136, 2, v49
	ds_read_b32 v233, v233
	v_lshl_add_u32 v234, v137, 2, v49
	ds_read_b32 v234, v234
	v_lshl_add_u32 v235, v138, 2, v49
	ds_read_b32 v235, v235
	v_lshl_add_u32 v236, v139, 2, v49
	ds_read_b32 v236, v236
	v_lshl_add_u32 v237, v140, 2, v49
	ds_read_b32 v237, v237
	v_lshl_add_u32 v238, v141, 2, v49
	ds_read_b32 v238, v238
	v_lshl_add_u32 v239, v142, 2, v49
	ds_read_b32 v239, v239
	v_lshl_add_u32 v240, v143, 2, v49
	ds_read_b32 v240, v240
	v_lshl_add_u32 v241, v144, 2, v49
	ds_read_b32 v241, v241
	v_lshl_add_u32 v242, v145, 2, v49
	ds_read_b32 v242, v242
	v_lshl_add_u32 v243, v146, 2, v49
	ds_read_b32 v243, v243
	v_lshl_add_u32 v244, v147, 2, v49
	ds_read_b32 v244, v244
	v_lshl_add_u32 v245, v165, 2, v49
	ds_read_b32 v245, v245
	v_lshl_add_u32 v246, v166, 2, v49
	ds_read_b32 v246, v246
	v_lshl_add_u32 v247, v167, 2, v49
	ds_read_b32 v247, v247
	v_lshl_add_u32 v250, v119, 1, v196
	v_add_u32_e32 v250, v250, v135
	s_waitcnt lgkmcnt(0)
	v_sub_f32_e32 v232, v232, v50
	v_mul_f32_e32 v232, 0x3fb8aa3b, v232
	v_exp_f32_e32 v232, v232
	v_sub_f32_e32 v233, v233, v50
	v_mul_f32_e32 v233, 0x3fb8aa3b, v233
	v_exp_f32_e32 v233, v233
	v_sub_f32_e32 v234, v234, v50
	v_mul_f32_e32 v234, 0x3fb8aa3b, v234
	v_exp_f32_e32 v234, v234
	v_sub_f32_e32 v235, v235, v50
	v_mul_f32_e32 v235, 0x3fb8aa3b, v235
	v_exp_f32_e32 v235, v235
	v_sub_f32_e32 v236, v236, v50
	v_mul_f32_e32 v236, 0x3fb8aa3b, v236
	v_exp_f32_e32 v236, v236
	v_sub_f32_e32 v237, v237, v50
	v_mul_f32_e32 v237, 0x3fb8aa3b, v237
	v_exp_f32_e32 v237, v237
	v_sub_f32_e32 v238, v238, v50
	v_mul_f32_e32 v238, 0x3fb8aa3b, v238
	v_exp_f32_e32 v238, v238
	v_sub_f32_e32 v239, v239, v50
	v_mul_f32_e32 v239, 0x3fb8aa3b, v239
	v_exp_f32_e32 v239, v239
	v_sub_f32_e32 v240, v240, v50
	v_mul_f32_e32 v240, 0x3fb8aa3b, v240
	v_exp_f32_e32 v240, v240
	v_sub_f32_e32 v241, v241, v50
	v_mul_f32_e32 v241, 0x3fb8aa3b, v241
	v_exp_f32_e32 v241, v241
	v_sub_f32_e32 v242, v242, v50
	v_mul_f32_e32 v242, 0x3fb8aa3b, v242
	v_exp_f32_e32 v242, v242
	v_sub_f32_e32 v243, v243, v50
	v_mul_f32_e32 v243, 0x3fb8aa3b, v243
	v_exp_f32_e32 v243, v243
	v_sub_f32_e32 v244, v244, v50
	v_mul_f32_e32 v244, 0x3fb8aa3b, v244
	v_exp_f32_e32 v244, v244
	v_sub_f32_e32 v245, v245, v50
	v_mul_f32_e32 v245, 0x3fb8aa3b, v245
	v_exp_f32_e32 v245, v245
	v_sub_f32_e32 v246, v246, v50
	v_mul_f32_e32 v246, 0x3fb8aa3b, v246
	v_exp_f32_e32 v246, v246
	v_sub_f32_e32 v247, v247, v50
	v_mul_f32_e32 v247, 0x3fb8aa3b, v247
	v_exp_f32_e32 v247, v247
	s_nop 0
	v_mul_f32_e32 v232, v32, v232
	v_mul_f32_e32 v233, v33, v233
	v_mul_f32_e32 v234, v34, v234
	v_mul_f32_e32 v235, v35, v235
	v_mul_f32_e32 v236, v36, v236
	v_mul_f32_e32 v237, v37, v237
	v_mul_f32_e32 v238, v38, v238
	v_mul_f32_e32 v239, v39, v239
	v_mul_f32_e32 v240, v40, v240
	v_mul_f32_e32 v241, v41, v241
	v_mul_f32_e32 v242, v42, v242
	v_mul_f32_e32 v243, v43, v243
	v_mul_f32_e32 v244, v44, v244
	v_mul_f32_e32 v245, v45, v245
	v_mul_f32_e32 v246, v46, v246
	v_mul_f32_e32 v247, v47, v247
	v_cndmask_b32_e64 v232, 0, v232, s[46:47]
	v_cndmask_b32_e64 v233, 0, v233, s[48:49]
	v_cndmask_b32_e64 v234, 0, v234, s[50:51]
	v_cndmask_b32_e64 v235, 0, v235, s[52:53]
	v_cndmask_b32_e64 v236, 0, v236, s[54:55]
	v_cndmask_b32_e64 v237, 0, v237, s[56:57]
	v_cndmask_b32_e64 v238, 0, v238, s[58:59]
	v_cndmask_b32_e64 v239, 0, v239, s[60:61]
	v_cndmask_b32_e64 v240, 0, v240, s[62:63]
	v_cndmask_b32_e64 v241, 0, v241, s[64:65]
	v_cndmask_b32_e64 v242, 0, v242, s[66:67]
	v_cndmask_b32_e64 v243, 0, v243, s[68:69]
	v_cndmask_b32_e64 v244, 0, v244, s[70:71]
	v_cndmask_b32_e64 v245, 0, v245, s[72:73]
	v_cndmask_b32_e64 v246, 0, v246, s[74:75]
	v_cndmask_b32_e64 v247, 0, v247, s[76:77]
	v_bfe_u32 v251, v232, 16, 1
	v_add3_u32 v251, v232, v251, s26
	ds_write_b16_d16_hi v250, v251
	v_bfe_u32 v251, v233, 16, 1
	v_add3_u32 v251, v233, v251, s26
	ds_write_b16_d16_hi v250, v251 offset:144
	v_bfe_u32 v251, v234, 16, 1
	v_add3_u32 v251, v234, v251, s26
	ds_write_b16_d16_hi v250, v251 offset:288
	v_bfe_u32 v251, v235, 16, 1
	v_add3_u32 v251, v235, v251, s26
	ds_write_b16_d16_hi v250, v251 offset:432
	v_bfe_u32 v251, v236, 16, 1
	v_add3_u32 v251, v236, v251, s26
	ds_write_b16_d16_hi v250, v251 offset:1152
	v_bfe_u32 v251, v237, 16, 1
	v_add3_u32 v251, v237, v251, s26
	ds_write_b16_d16_hi v250, v251 offset:1296
	v_bfe_u32 v251, v238, 16, 1
	v_add3_u32 v251, v238, v251, s26
	ds_write_b16_d16_hi v250, v251 offset:1440
	v_bfe_u32 v251, v239, 16, 1
	v_add3_u32 v251, v239, v251, s26
	ds_write_b16_d16_hi v250, v251 offset:1584
	v_bfe_u32 v251, v240, 16, 1
	v_add3_u32 v251, v240, v251, s26
	ds_write_b16_d16_hi v250, v251 offset:2304
	v_bfe_u32 v251, v241, 16, 1
	v_add3_u32 v251, v241, v251, s26
	ds_write_b16_d16_hi v250, v251 offset:2448
	v_bfe_u32 v251, v242, 16, 1
	v_add3_u32 v251, v242, v251, s26
	ds_write_b16_d16_hi v250, v251 offset:2592
	v_bfe_u32 v251, v243, 16, 1
	v_add3_u32 v251, v243, v251, s26
	ds_write_b16_d16_hi v250, v251 offset:2736
	v_bfe_u32 v251, v244, 16, 1
	v_add3_u32 v251, v244, v251, s26
	ds_write_b16_d16_hi v250, v251 offset:3456
	v_bfe_u32 v251, v245, 16, 1
	v_add3_u32 v251, v245, v251, s26
	ds_write_b16_d16_hi v250, v251 offset:3600
	v_bfe_u32 v251, v246, 16, 1
	v_add3_u32 v251, v246, v251, s26
	ds_write_b16_d16_hi v250, v251 offset:3744
	v_mov_b32_e32 v33, v247
	v_mov_b32_e32 v32, v250
	s_mov_b64 s[84:85], exec
	s_branch .LBB0_751
